# e38: e33 + grid-barrier leaders issue their acquire invalidate right after the top-level arrival returns (before polling), so it is off the release chain
# speedup vs baseline: 1.0020x; 1.0020x over previous
; __device__ __forceinline__ unsigned xb_ld(unsigned* p)              { return __hip_atomic_load(p, __ATOMIC_RELAXED, __HIP_MEMORY_SCOPE_AGENT); }
; __device__ __forceinline__ unsigned xb_add(unsigned* p, unsigned v) { return __hip_atomic_fetch_add(p, v, __ATOMIC_RELAXED, __HIP_MEMORY_SCOPE_AGENT); }
; #define XB_SPIN(cond, bar) do { unsigned _sp = 0; while (cond) { __builtin_amdgcn_s_sleep(1); \
;     if ((++_sp & 255u) == 0u) { if (xb_ld(&(bar)[XB_TMO])) break; if (_sp > XB_SPIN_CAP) { atomicAdd(&(bar)[XB_TMO], 1u); break; } } } } while (0)
; __device__ __forceinline__ void xcd_barrier(const XcdBarrier& b) {
;     ...
;         const unsigned old = xb_add(&bar[XB_XSUB(b.x)], 1u);
;         const unsigned gen = old / nloc;
;         if (old + 1u == (gen + 1u) * nloc) {
;             __builtin_amdgcn_fence(__ATOMIC_RELEASE, "agent");
;             asm volatile("s_waitcnt vmcnt(0)" ::: "memory");
;             const unsigned og = xb_add(&bar[XB_TOP], 1u);
;             const unsigned tg = og / nx;
;             if (og + 1u == (tg + 1u) * nx) xb_add(&bar[XB_TOPGEN], 1u);
;             else XB_SPIN(xb_ld(&bar[XB_TOPGEN]) == tg, bar);
;             __builtin_amdgcn_fence(__ATOMIC_ACQUIRE, "agent");
.LBB0_114:
	s_or_b64 exec, exec, s[10:11]
	v_cvt_f32_u32_e32 v4, v1
	s_waitcnt vmcnt(0)
	v_readfirstlane_b32 s0, v3
	buffer_inv sc1
	s_add_u32 s10, s50, 0x3500
	s_addc_u32 s11, s51, 0
	v_rcp_iflag_f32_e32 v4, v4
	v_add_u32_e32 v2, s0, v2
	v_add_u32_e32 v5, 1, v2
	s_mov_b64 s[12:13], -1
	v_mul_f32_e32 v3, 0x4f7ffffe, v4
	v_cvt_u32_f32_e32 v3, v3
	v_sub_u32_e32 v4, 0, v1
	v_mul_lo_u32 v4, v4, v3
	v_mul_hi_u32 v4, v3, v4
	v_add_u32_e32 v3, v3, v4
	v_mul_hi_u32 v3, v2, v3
	v_mul_lo_u32 v4, v3, v1
	v_sub_u32_e32 v2, v2, v4
	v_add_u32_e32 v6, 1, v3
	v_cmp_ge_u32_e32 vcc, v2, v1
	v_sub_u32_e32 v4, v2, v1
	s_nop 0
	v_cndmask_b32_e32 v3, v3, v6, vcc
	v_cndmask_b32_e32 v2, v2, v4, vcc
	v_add_u32_e32 v4, 1, v3
	v_cmp_ge_u32_e32 vcc, v2, v1
	s_nop 1
	v_cndmask_b32_e32 v4, v3, v4, vcc
	v_mul_lo_u32 v2, v1, v4
	v_add_u32_e32 v1, v2, v1
	v_cmp_ne_u32_e32 vcc, v5, v1
	v_mov_b64_e32 v[2:3], s[10:11]
	s_and_saveexec_b64 s[8:9], vcc
	s_cbranch_execz .LBB0_126
	v_mov_b32_e32 v1, 0
	global_load_dword v2, v1, s[10:11] sc1
	s_mov_b64 s[20:21], 0
	s_waitcnt vmcnt(0)
	v_cmp_eq_u32_e32 vcc, v2, v4
	s_and_saveexec_b64 s[14:15], vcc
	s_cbranch_execz .LBB0_125
	s_add_u32 s12, s50, 0x200
	s_addc_u32 s13, s51, 0
	s_mov_b32 s0, 1
	s_branch .LBB0_118

; __device__ __forceinline__ unsigned xb_ld(unsigned* p)              { return __hip_atomic_load(p, __ATOMIC_RELAXED, __HIP_MEMORY_SCOPE_AGENT); }
; __device__ __forceinline__ unsigned xb_add(unsigned* p, unsigned v) { return __hip_atomic_fetch_add(p, v, __ATOMIC_RELAXED, __HIP_MEMORY_SCOPE_AGENT); }
; #define XB_SPIN(cond, bar) do { unsigned _sp = 0; while (cond) { __builtin_amdgcn_s_sleep(1); \
;     if ((++_sp & 255u) == 0u) { if (xb_ld(&(bar)[XB_TMO])) break; if (_sp > XB_SPIN_CAP) { atomicAdd(&(bar)[XB_TMO], 1u); break; } } } } while (0)
; __device__ __forceinline__ void xcd_barrier(const XcdBarrier& b) {
;     ...
;             const unsigned og = xb_add(&bar[XB_TOP], 1u);
;             const unsigned tg = og / nx;
;             if (og + 1u == (tg + 1u) * nx) xb_add(&bar[XB_TOPGEN], 1u);
;             else XB_SPIN(xb_ld(&bar[XB_TOPGEN]) == tg, bar);
;             __builtin_amdgcn_fence(__ATOMIC_ACQUIRE, "agent");
;             xb_add(&bar[XB_XGEN(b.x)], 1u);
;             asm volatile("s_waitcnt vmcnt(0)" ::: "memory");
.LBB0_128:
	s_or_b64 exec, exec, s[8:9]
	s_mov_b64 s[8:9], exec
	v_mbcnt_lo_u32_b32 v1, s8, 0
	v_mbcnt_hi_u32_b32 v1, s9, v1
	v_cmp_eq_u32_e32 vcc, 0, v1
	s_waitcnt vmcnt(0)
	s_and_saveexec_b64 s[10:11], vcc
	s_cbranch_execz .LBB0_130
	s_bcnt1_i32_b64 s0, s[8:9]
	v_mov_b32_e32 v1, 0x2000
	v_mov_b32_e32 v2, s0
	global_atomic_add v1, v2, s[6:7] offset:1024

; __device__ __forceinline__ unsigned xb_ld(unsigned* p)              { return __hip_atomic_load(p, __ATOMIC_RELAXED, __HIP_MEMORY_SCOPE_AGENT); }
; __device__ __forceinline__ unsigned xb_add(unsigned* p, unsigned v) { return __hip_atomic_fetch_add(p, v, __ATOMIC_RELAXED, __HIP_MEMORY_SCOPE_AGENT); }
; #define XB_SPIN(cond, bar) do { unsigned _sp = 0; while (cond) { __builtin_amdgcn_s_sleep(1); \
;     if ((++_sp & 255u) == 0u) { if (xb_ld(&(bar)[XB_TMO])) break; if (_sp > XB_SPIN_CAP) { atomicAdd(&(bar)[XB_TMO], 1u); break; } } } } while (0)
; __device__ __forceinline__ void xcd_barrier(const XcdBarrier& b) {
;     ...
;         const unsigned old = xb_add(&bar[XB_XSUB(b.x)], 1u);
;         const unsigned gen = old / nloc;
;         if (old + 1u == (gen + 1u) * nloc) {
;             __builtin_amdgcn_fence(__ATOMIC_RELEASE, "agent");
;             asm volatile("s_waitcnt vmcnt(0)" ::: "memory");
;             const unsigned og = xb_add(&bar[XB_TOP], 1u);
;             const unsigned tg = og / nx;
;             if (og + 1u == (tg + 1u) * nx) xb_add(&bar[XB_TOPGEN], 1u);
;             else XB_SPIN(xb_ld(&bar[XB_TOPGEN]) == tg, bar);
;             __builtin_amdgcn_fence(__ATOMIC_ACQUIRE, "agent");
.LBB0_1033:
	s_or_b64 exec, exec, s[8:9]
	v_cvt_f32_u32_e32 v4, v1
	s_waitcnt vmcnt(0)
	v_readfirstlane_b32 s0, v3
	buffer_inv sc1
	s_add_u32 s8, s50, 0x3500
	s_addc_u32 s9, s51, 0
	v_rcp_iflag_f32_e32 v4, v4
	v_add_u32_e32 v2, s0, v2
	v_add_u32_e32 v5, 1, v2
	s_mov_b64 s[10:11], -1
	v_mul_f32_e32 v3, 0x4f7ffffe, v4
	v_cvt_u32_f32_e32 v3, v3
	v_sub_u32_e32 v4, 0, v1
	v_mul_lo_u32 v4, v4, v3
	v_mul_hi_u32 v4, v3, v4
	v_add_u32_e32 v3, v3, v4
	v_mul_hi_u32 v3, v2, v3
	v_mul_lo_u32 v4, v3, v1
	v_sub_u32_e32 v2, v2, v4
	v_add_u32_e32 v6, 1, v3
	v_cmp_ge_u32_e32 vcc, v2, v1
	v_sub_u32_e32 v4, v2, v1
	s_nop 0
	v_cndmask_b32_e32 v3, v3, v6, vcc
	v_cndmask_b32_e32 v2, v2, v4, vcc
	v_add_u32_e32 v4, 1, v3
	v_cmp_ge_u32_e32 vcc, v2, v1
	s_nop 1
	v_cndmask_b32_e32 v4, v3, v4, vcc
	v_mul_lo_u32 v2, v1, v4
	v_add_u32_e32 v1, v2, v1
	v_cmp_ne_u32_e32 vcc, v5, v1
	v_mov_b64_e32 v[2:3], s[8:9]
	s_and_saveexec_b64 s[6:7], vcc
	s_cbranch_execz .LBB0_1045
	v_mov_b32_e32 v1, 0
	global_load_dword v2, v1, s[8:9] sc1
	s_mov_b64 s[14:15], 0
	s_waitcnt vmcnt(0)
	v_cmp_eq_u32_e32 vcc, v2, v4
	s_and_saveexec_b64 s[12:13], vcc
	s_cbranch_execz .LBB0_1044
	s_add_u32 s10, s50, 0x200
	s_addc_u32 s11, s51, 0
	s_mov_b32 s0, 1
	s_branch .LBB0_1037

; __device__ __forceinline__ unsigned xb_ld(unsigned* p)              { return __hip_atomic_load(p, __ATOMIC_RELAXED, __HIP_MEMORY_SCOPE_AGENT); }
; __device__ __forceinline__ unsigned xb_add(unsigned* p, unsigned v) { return __hip_atomic_fetch_add(p, v, __ATOMIC_RELAXED, __HIP_MEMORY_SCOPE_AGENT); }
; #define XB_SPIN(cond, bar) do { unsigned _sp = 0; while (cond) { __builtin_amdgcn_s_sleep(1); \
;     if ((++_sp & 255u) == 0u) { if (xb_ld(&(bar)[XB_TMO])) break; if (_sp > XB_SPIN_CAP) { atomicAdd(&(bar)[XB_TMO], 1u); break; } } } } while (0)
; __device__ __forceinline__ void xcd_barrier(const XcdBarrier& b) {
;     ...
;             const unsigned og = xb_add(&bar[XB_TOP], 1u);
;             const unsigned tg = og / nx;
;             if (og + 1u == (tg + 1u) * nx) xb_add(&bar[XB_TOPGEN], 1u);
;             else XB_SPIN(xb_ld(&bar[XB_TOPGEN]) == tg, bar);
;             __builtin_amdgcn_fence(__ATOMIC_ACQUIRE, "agent");
;             xb_add(&bar[XB_XGEN(b.x)], 1u);
;             asm volatile("s_waitcnt vmcnt(0)" ::: "memory");
.LBB0_1047:
	s_or_b64 exec, exec, s[6:7]
	s_mov_b64 s[6:7], exec
	v_mbcnt_lo_u32_b32 v1, s6, 0
	v_mbcnt_hi_u32_b32 v1, s7, v1
	v_cmp_eq_u32_e32 vcc, 0, v1
	s_waitcnt vmcnt(0)
	s_and_saveexec_b64 s[8:9], vcc
	s_cbranch_execz .LBB0_1049
	s_bcnt1_i32_b64 s0, s[6:7]
	v_mov_b32_e32 v1, 0x2000
	v_mov_b32_e32 v2, s0
	global_atomic_add v1, v2, s[4:5] offset:1024
